# final RMSNorm rows remapped batch->XCD; last seam XCD-local so final norm overlaps other XCDs' compute
# speedup vs baseline: 1.0044x; 1.0044x over previous
.LBB0_1287:
	v_readlane_b32 s100, v255, 40
	s_nop 3
	s_cmp_eq_u32 s100, 0
	s_cbranch_scc1 .Lfb_slow_10
	v_readlane_b32 s100, v255, 41
	v_readlane_b32 s101, v255, 42
	v_mov_b32_e32 v2, 0
	v_mov_b32_e32 v3, 1
	v_mov_b32_e32 v4, 1
	s_nop 2
	global_atomic_add v3, v2, v3, s[100:101] sc0
	s_waitcnt vmcnt(0)
	v_readfirstlane_b32 vcc_hi, v3
	s_nop 3
	s_lshr_b32 vcc_lo, vcc_hi, 5
	s_add_i32 vcc_hi, vcc_hi, 1
	s_and_b32 vcc_hi, vcc_hi, 31
	s_cmp_lg_u32 vcc_hi, 0
	s_cbranch_scc1 .Lfb_spin_10
	global_atomic_add v2, v4, s[100:101] offset:128
	s_branch .Lfb_done_10

.LBB0_1337:
	s_lshl_b32 s1, s97, 3
	v_readfirstlane_b32 s0, v218
	s_ashr_i32 s0, s0, 6
	s_add_i32 s4, s0, s1
	s_cmp_lt_i32 s4, 0x8000
	s_cbranch_scc0 .LBB0_1340
	s_load_dwordx2 s[6:7], s[78:79], 0xe0
	s_load_dwordx4 s[0:3], s[78:79], 0xe8
	v_and_b32_e32 v18, 63, v218
	v_lshlrev_b32_e32 v16, 4, v18
	v_mov_b32_e32 v17, 0
	s_waitcnt lgkmcnt(0)
	global_load_dwordx4 v[0:3], v16, s[6:7] offset:3072
	global_load_dwordx4 v[4:7], v16, s[6:7] offset:2048
	global_load_dwordx4 v[8:11], v16, s[6:7] offset:1024
	global_load_dwordx4 v[12:15], v16, s[6:7]
	s_lshl_b32 s6, s76, 3
	s_add_u32 s16, s2, 0x1f200000
	v_lshlrev_b32_e32 v18, 3, v18
	v_mov_b32_e32 v19, v17
	s_addc_u32 s17, s3, 0
	v_lshl_add_u64 v[18:19], s[2:3], 0, v[18:19]
	s_mov_b64 s[2:3], 0x9700000
	s_ashr_i32 s7, s6, 31
	v_lshl_add_u64 v[18:19], v[18:19], 0, s[2:3]
	v_lshl_add_u64 v[20:21], s[0:1], 0, v[16:17]
	s_lshl_b32 s18, s76, 5
	s_lshl_b32 s19, s76, 4
	s_mul_i32 s20, s76, 24
	v_mov_b32_e32 v36, 0x358637bd
	s_mov_b32 s21, 0x800000
	s_movk_i32 s101, 0x7fff
	v_readlane_b32 s100, v255, 40
	s_nop 3
	s_cmp_eq_u32 s100, 0
	s_cbranch_scc1 .Lfn_noremap
	s_and_b32 s100, s97, 7
	s_lshl_b32 s100, s100, 12
	s_add_i32 s101, s100, 0xfff
	s_lshr_b32 s4, s97, 3
	s_lshl_b32 s4, s4, 3
	s_or_b32 s4, s4, s100
	v_readfirstlane_b32 s100, v218
	s_nop 3
	s_lshr_b32 s100, s100, 6
	s_or_b32 s4, s4, s100
	s_movk_i32 s6, 0x100
	s_movk_i32 s19, 0x200
	s_movk_i32 s20, 0x300
	s_movk_i32 s18, 0x400
.Lfn_noremap:
	s_lshl_b64 s[8:9], s[6:7], 3
.LBB0_1339:
	s_ashr_i32 s5, s4, 31
	s_lshl_b64 s[0:1], s[4:5], 3
	s_add_u32 s0, s16, s0
	s_addc_u32 s1, s17, s1
	s_add_i32 s14, s6, s4
	global_load_dwordx2 v[38:39], v17, s[0:1]
	s_lshl_b64 s[2:3], s[4:5], 11
	s_ashr_i32 s15, s14, 31
	s_add_u32 s0, s0, s8
	s_addc_u32 s1, s1, s9
	s_add_i32 s12, s19, s4
	global_load_dwordx2 v[42:43], v17, s[0:1]
	s_ashr_i32 s13, s12, 31
	v_lshl_add_u64 v[22:23], v[18:19], 0, s[2:3]
	s_lshl_b64 s[0:1], s[14:15], 11
	s_lshl_b64 s[2:3], s[12:13], 3
	s_add_u32 s2, s16, s2
	s_addc_u32 s3, s17, s3
	global_load_dwordx2 v[44:45], v17, s[2:3]
	s_add_i32 s10, s20, s4
	s_ashr_i32 s11, s10, 31
	s_lshl_b64 s[2:3], s[12:13], 11
	s_lshl_b64 s[22:23], s[10:11], 3
	s_add_u32 s22, s16, s22
	s_addc_u32 s23, s17, s23
	global_load_dwordx2 v[40:41], v[22:23], off nt
	global_load_dwordx2 v[46:47], v17, s[22:23]
	global_load_dwordx2 v[48:49], v[22:23], off offset:512 nt
	global_load_dwordx2 v[50:51], v[22:23], off offset:1024 nt
	global_load_dwordx2 v[52:53], v[22:23], off offset:1536 nt
	v_lshl_add_u64 v[22:23], v[18:19], 0, s[0:1]
	global_load_dwordx2 v[54:55], v[22:23], off nt
	global_load_dwordx2 v[56:57], v[22:23], off offset:512 nt
	global_load_dwordx2 v[58:59], v[22:23], off offset:1024 nt
	global_load_dwordx2 v[60:61], v[22:23], off offset:1536 nt
	v_lshl_add_u64 v[22:23], v[18:19], 0, s[2:3]
	global_load_dwordx2 v[62:63], v[22:23], off nt
	global_load_dwordx2 v[34:35], v[22:23], off offset:512 nt
	global_load_dwordx2 v[32:33], v[22:23], off offset:1024 nt
	global_load_dwordx2 v[28:29], v[22:23], off offset:1536 nt
	s_lshl_b64 s[0:1], s[10:11], 11
	v_lshl_add_u64 v[64:65], v[18:19], 0, s[0:1]
	global_load_dwordx2 v[30:31], v[64:65], off nt
	global_load_dwordx2 v[26:27], v[64:65], off offset:512 nt
	global_load_dwordx2 v[24:25], v[64:65], off offset:1024 nt
	global_load_dwordx2 v[22:23], v[64:65], off offset:1536 nt
	s_lshl_b64 s[2:3], s[4:5], 12
	v_lshl_add_u64 v[66:67], v[20:21], 0, s[2:3]
	s_add_i32 s4, s4, s18
	s_waitcnt vmcnt(19)
	v_ffbh_u32_e32 v16, v39
	v_min_u32_e32 v16, 32, v16
	v_lshlrev_b64 v[38:39], v16, v[38:39]
	v_min_u32_e32 v37, 1, v38
	v_or_b32_e32 v37, v39, v37
	v_cvt_f32_u32_e32 v37, v37
	s_waitcnt vmcnt(18)
	v_ffbh_u32_e32 v38, v43
	v_min_u32_e32 v68, 32, v38
	v_lshlrev_b64 v[38:39], v68, v[42:43]
	v_min_u32_e32 v38, 1, v38
	v_or_b32_e32 v38, v39, v38
	v_sub_u32_e32 v16, 32, v16
	v_sub_u32_e32 v42, 32, v68
	s_waitcnt vmcnt(17)
	v_ffbh_u32_e32 v39, v45
	v_cvt_f32_u32_e32 v43, v38
	v_min_u32_e32 v68, 32, v39
	v_ldexp_f32 v16, v37, v16
	v_lshlrev_b64 v[38:39], v68, v[44:45]
	v_fmamk_f32 v16, v16, 0x31800000, v36
	v_min_u32_e32 v38, 1, v38
	v_mul_f32_e32 v44, 0x4b800000, v16
	v_or_b32_e32 v38, v39, v38
	s_waitcnt vmcnt(15)
	v_ffbh_u32_e32 v39, v47
	v_cmp_gt_f32_e32 vcc, s21, v16
	v_ldexp_f32 v42, v43, v42
	v_cvt_f32_u32_e32 v43, v38
	v_cndmask_b32_e32 v16, v16, v44, vcc
	v_min_u32_e32 v44, 32, v39
	v_lshlrev_b64 v[38:39], v44, v[46:47]
	v_rsq_f32_e32 v16, v16
	v_min_u32_e32 v38, 1, v38
	v_sub_u32_e32 v37, 32, v68
	v_or_b32_e32 v38, v39, v38
	v_fmamk_f32 v42, v42, 0x31800000, v36
	v_ldexp_f32 v37, v43, v37
	v_cvt_f32_u32_e32 v43, v38
	v_mul_f32_e32 v45, 0x4b800000, v42
	v_cmp_gt_f32_e64 s[0:1], s21, v42
	v_mul_f32_e32 v38, 0x45800000, v16
	v_lshlrev_b32_e32 v64, 16, v40
	v_cndmask_b32_e64 v42, v42, v45, s[0:1]
	v_and_b32_e32 v65, 0xffff0000, v40
	v_sub_u32_e32 v44, 32, v44
	v_rsq_f32_e32 v45, v42
	v_cndmask_b32_e32 v42, v16, v38, vcc
	v_pk_mul_f32 v[38:39], v[42:43], v[64:65] op_sel_hi:[0,1]
	v_ldexp_f32 v43, v43, v44
	v_fmamk_f32 v43, v43, 0x31800000, v36
	v_mul_f32_e32 v44, 0x4b800000, v43
	v_cmp_gt_f32_e64 s[2:3], s21, v43
	v_lshlrev_b32_e32 v40, 16, v41
	v_and_b32_e32 v41, 0xffff0000, v41
	v_cndmask_b32_e64 v43, v43, v44, s[2:3]
	v_rsq_f32_e32 v43, v43
	v_pk_mul_f32 v[38:39], v[12:13], v[38:39]
	v_fmamk_f32 v37, v37, 0x31800000, v36
	v_mul_f32_e32 v16, 0x4b800000, v37
	v_pk_mul_f32 v[40:41], v[42:43], v[40:41] op_sel_hi:[0,1]
	v_pk_mul_f32 v[40:41], v[14:15], v[40:41]
	global_store_dwordx4 v[66:67], v[38:41], off nt
	v_cmp_gt_f32_e32 vcc, s21, v37
	s_waitcnt vmcnt(15)
	v_lshlrev_b32_e32 v38, 16, v48
	v_and_b32_e32 v39, 0xffff0000, v48
	v_lshlrev_b32_e32 v40, 16, v49
	v_and_b32_e32 v41, 0xffff0000, v49
	v_pk_mul_f32 v[38:39], v[42:43], v[38:39] op_sel_hi:[0,1]
	v_pk_mul_f32 v[40:41], v[42:43], v[40:41] op_sel_hi:[0,1]
	v_pk_mul_f32 v[38:39], v[8:9], v[38:39]
	v_pk_mul_f32 v[40:41], v[10:11], v[40:41]
	global_store_dwordx4 v[66:67], v[38:41], off offset:1024 nt
	v_cndmask_b32_e32 v16, v37, v16, vcc
	v_rsq_f32_e32 v16, v16
	s_waitcnt vmcnt(15)
	v_lshlrev_b32_e32 v38, 16, v50
	v_and_b32_e32 v39, 0xffff0000, v50
	v_lshlrev_b32_e32 v40, 16, v51
	v_and_b32_e32 v41, 0xffff0000, v51
	v_pk_mul_f32 v[38:39], v[42:43], v[38:39] op_sel_hi:[0,1]
	v_pk_mul_f32 v[40:41], v[42:43], v[40:41] op_sel_hi:[0,1]
	v_pk_mul_f32 v[38:39], v[4:5], v[38:39]
	v_pk_mul_f32 v[40:41], v[6:7], v[40:41]
	global_store_dwordx4 v[66:67], v[38:41], off offset:2048 nt
	v_mul_f32_e32 v37, 0x45800000, v45
	v_cndmask_b32_e64 v44, v45, v37, s[0:1]
	s_waitcnt vmcnt(15)
	v_lshlrev_b32_e32 v38, 16, v52
	v_and_b32_e32 v39, 0xffff0000, v52
	v_lshlrev_b32_e32 v40, 16, v53
	v_and_b32_e32 v41, 0xffff0000, v53
	v_pk_mul_f32 v[38:39], v[42:43], v[38:39] op_sel_hi:[0,1]
	v_pk_mul_f32 v[40:41], v[42:43], v[40:41] op_sel_hi:[0,1]
	v_pk_mul_f32 v[38:39], v[0:1], v[38:39]
	v_pk_mul_f32 v[40:41], v[2:3], v[40:41]
	v_mul_f32_e32 v37, 0x45800000, v16
	global_store_dwordx4 v[66:67], v[38:41], off offset:3072 nt
	v_cndmask_b32_e32 v46, v16, v37, vcc
	v_mul_f32_e32 v16, 0x45800000, v43
	s_waitcnt vmcnt(15)
	v_lshlrev_b32_e32 v38, 16, v54
	v_and_b32_e32 v39, 0xffff0000, v54
	v_lshlrev_b32_e32 v40, 16, v55
	v_and_b32_e32 v41, 0xffff0000, v55
	s_lshl_b64 s[0:1], s[14:15], 12
	v_pk_mul_f32 v[38:39], v[44:45], v[38:39] op_sel_hi:[0,1]
	v_pk_mul_f32 v[40:41], v[44:45], v[40:41] op_sel_hi:[0,1]
	v_cndmask_b32_e64 v16, v43, v16, s[2:3]
	v_lshl_add_u64 v[42:43], v[20:21], 0, s[0:1]
	v_pk_mul_f32 v[38:39], v[12:13], v[38:39]
	v_pk_mul_f32 v[40:41], v[14:15], v[40:41]
	global_store_dwordx4 v[42:43], v[38:41], off nt
	s_lshl_b64 s[0:1], s[12:13], 12
	s_waitcnt vmcnt(15)
	v_lshlrev_b32_e32 v38, 16, v56
	v_and_b32_e32 v39, 0xffff0000, v56
	v_lshlrev_b32_e32 v40, 16, v57
	v_and_b32_e32 v41, 0xffff0000, v57
	v_pk_mul_f32 v[38:39], v[44:45], v[38:39] op_sel_hi:[0,1]
	v_pk_mul_f32 v[40:41], v[44:45], v[40:41] op_sel_hi:[0,1]
	v_pk_mul_f32 v[38:39], v[8:9], v[38:39]
	v_pk_mul_f32 v[40:41], v[10:11], v[40:41]
	global_store_dwordx4 v[42:43], v[38:41], off offset:1024 nt
	s_waitcnt vmcnt(15)
	s_nop 0
	v_lshlrev_b32_e32 v38, 16, v58
	v_and_b32_e32 v39, 0xffff0000, v58
	v_lshlrev_b32_e32 v40, 16, v59
	v_and_b32_e32 v41, 0xffff0000, v59
	v_pk_mul_f32 v[38:39], v[44:45], v[38:39] op_sel_hi:[0,1]
	v_pk_mul_f32 v[40:41], v[44:45], v[40:41] op_sel_hi:[0,1]
	v_pk_mul_f32 v[38:39], v[4:5], v[38:39]
	v_pk_mul_f32 v[40:41], v[6:7], v[40:41]
	global_store_dwordx4 v[42:43], v[38:41], off offset:2048 nt
	s_waitcnt vmcnt(15)
	s_nop 0
	v_lshlrev_b32_e32 v38, 16, v60
	v_and_b32_e32 v39, 0xffff0000, v60
	v_lshlrev_b32_e32 v40, 16, v61
	v_and_b32_e32 v41, 0xffff0000, v61
	v_pk_mul_f32 v[38:39], v[44:45], v[38:39] op_sel_hi:[0,1]
	v_pk_mul_f32 v[40:41], v[44:45], v[40:41] op_sel_hi:[0,1]
	v_pk_mul_f32 v[38:39], v[0:1], v[38:39]
	v_pk_mul_f32 v[40:41], v[2:3], v[40:41]
	global_store_dwordx4 v[42:43], v[38:41], off offset:3072 nt
	v_lshl_add_u64 v[42:43], v[20:21], 0, s[0:1]
	s_lshl_b64 s[0:1], s[10:11], 12
	s_waitcnt vmcnt(15)
	v_lshlrev_b32_e32 v38, 16, v62
	v_and_b32_e32 v39, 0xffff0000, v62
	v_lshlrev_b32_e32 v40, 16, v63
	v_and_b32_e32 v41, 0xffff0000, v63
	v_pk_mul_f32 v[38:39], v[46:47], v[38:39] op_sel_hi:[0,1]
	v_pk_mul_f32 v[40:41], v[46:47], v[40:41] op_sel_hi:[0,1]
	v_pk_mul_f32 v[38:39], v[12:13], v[38:39]
	v_pk_mul_f32 v[40:41], v[14:15], v[40:41]
	global_store_dwordx4 v[42:43], v[38:41], off nt
	s_cmp_gt_i32 s4, s101
	s_waitcnt vmcnt(15)
	v_lshlrev_b32_e32 v38, 16, v34
	v_and_b32_e32 v39, 0xffff0000, v34
	v_lshlrev_b32_e32 v34, 16, v35
	v_and_b32_e32 v35, 0xffff0000, v35
	v_pk_mul_f32 v[34:35], v[46:47], v[34:35] op_sel_hi:[0,1]
	v_pk_mul_f32 v[38:39], v[46:47], v[38:39] op_sel_hi:[0,1]
	v_pk_mul_f32 v[40:41], v[10:11], v[34:35]
	s_waitcnt vmcnt(14)
	v_lshlrev_b32_e32 v34, 16, v32
	v_and_b32_e32 v35, 0xffff0000, v32
	v_lshlrev_b32_e32 v32, 16, v33
	v_and_b32_e32 v33, 0xffff0000, v33
	v_pk_mul_f32 v[38:39], v[8:9], v[38:39]
	v_pk_mul_f32 v[32:33], v[46:47], v[32:33] op_sel_hi:[0,1]
	global_store_dwordx4 v[42:43], v[38:41], off offset:1024 nt
	v_pk_mul_f32 v[34:35], v[46:47], v[34:35] op_sel_hi:[0,1]
	s_nop 0
	v_pk_mul_f32 v[40:41], v[6:7], v[32:33]
	s_waitcnt vmcnt(14)
	v_lshlrev_b32_e32 v32, 16, v28
	v_and_b32_e32 v33, 0xffff0000, v28
	v_lshlrev_b32_e32 v28, 16, v29
	v_and_b32_e32 v29, 0xffff0000, v29
	v_pk_mul_f32 v[28:29], v[46:47], v[28:29] op_sel_hi:[0,1]
	v_pk_mul_f32 v[38:39], v[4:5], v[34:35]
	v_pk_mul_f32 v[32:33], v[46:47], v[32:33] op_sel_hi:[0,1]
	v_pk_mul_f32 v[34:35], v[2:3], v[28:29]
	s_waitcnt vmcnt(13)
	v_lshlrev_b32_e32 v28, 16, v30
	v_and_b32_e32 v29, 0xffff0000, v30
	v_lshlrev_b32_e32 v30, 16, v31
	v_and_b32_e32 v31, 0xffff0000, v31
	v_pk_mul_f32 v[32:33], v[0:1], v[32:33]
	v_pk_mul_f32 v[28:29], v[16:17], v[28:29] op_sel_hi:[0,1]
	v_pk_mul_f32 v[30:31], v[16:17], v[30:31] op_sel_hi:[0,1]
	global_store_dwordx4 v[42:43], v[32:35], off offset:3072 nt
	v_pk_mul_f32 v[28:29], v[12:13], v[28:29]
	v_pk_mul_f32 v[30:31], v[14:15], v[30:31]
	v_lshl_add_u64 v[32:33], v[20:21], 0, s[0:1]
	global_store_dwordx4 v[32:33], v[28:31], off nt
	global_store_dwordx4 v[42:43], v[38:41], off offset:2048 nt
	s_waitcnt vmcnt(15)
	v_lshlrev_b32_e32 v28, 16, v26
	v_and_b32_e32 v29, 0xffff0000, v26
	v_lshlrev_b32_e32 v26, 16, v27
	v_and_b32_e32 v27, 0xffff0000, v27
	v_pk_mul_f32 v[26:27], v[16:17], v[26:27] op_sel_hi:[0,1]
	v_pk_mul_f32 v[28:29], v[16:17], v[28:29] op_sel_hi:[0,1]
	v_pk_mul_f32 v[30:31], v[10:11], v[26:27]
	s_waitcnt vmcnt(14)
	v_lshlrev_b32_e32 v26, 16, v24
	v_and_b32_e32 v27, 0xffff0000, v24
	v_lshlrev_b32_e32 v24, 16, v25
	v_and_b32_e32 v25, 0xffff0000, v25
	v_pk_mul_f32 v[28:29], v[8:9], v[28:29]
	v_pk_mul_f32 v[24:25], v[16:17], v[24:25] op_sel_hi:[0,1]
	global_store_dwordx4 v[32:33], v[28:31], off offset:1024 nt
	v_pk_mul_f32 v[26:27], v[16:17], v[26:27] op_sel_hi:[0,1]
	v_pk_mul_f32 v[26:27], v[4:5], v[26:27]
	v_pk_mul_f32 v[28:29], v[6:7], v[24:25]
	s_waitcnt vmcnt(14)
	v_lshlrev_b32_e32 v24, 16, v22
	v_and_b32_e32 v25, 0xffff0000, v22
	v_lshlrev_b32_e32 v22, 16, v23
	v_and_b32_e32 v23, 0xffff0000, v23
	v_pk_mul_f32 v[24:25], v[16:17], v[24:25] op_sel_hi:[0,1]
	v_pk_mul_f32 v[22:23], v[16:17], v[22:23] op_sel_hi:[0,1]
	global_store_dwordx4 v[32:33], v[26:29], off offset:2048 nt
	v_pk_mul_f32 v[24:25], v[0:1], v[24:25]
	s_nop 0
	v_pk_mul_f32 v[26:27], v[2:3], v[22:23]
	global_store_dwordx4 v[32:33], v[24:27], off offset:3072 nt
	s_cbranch_scc0 .LBB0_1339
